# GLA G1 (per-chunk K^T V): next unit's V/K tile loads issued one unit ahead into a second register set; AL scale loads issued at unit start
# speedup vs baseline: 1.0056x; 1.0056x over previous
; #define LAS __attribute__((address_space(3)))
; __device__ __forceinline__ void ph_g1(Frame& F) {
;     const bf16* P = (const bf16*)(F.ws + WS_P); const bf16* KFg = (const bf16*)(F.ws + WS_KF); const bf16* KBg = (const bf16*)(F.ws + WS_KB); bf16* UT = (bf16*)(F.ws + WS_UT); const float* AL = (const float*)(F.ws + WS_AL);
;     LAS bf16* VT = (LAS bf16*)(F.lds + RING_OFF); LAS bf16* KH0 = VT + 128 * PITCH; LAS bf16* KH1 = KH0 + 64 * PITCH;
;     const int r32 = F.lane & 31, hi = F.lane >> 5, dir = F.wave >> 2, db = F.wave & 3;
;     for (int u = blockIdx.x; u < NRC * 8; u += F.G) {
;         const int rc = u >> 3, h = u & 7;
;         __syncthreads();
;         stage_vt(F, P, rc, h, VT);
;         {
;             const int half = F.tid >> 8, tl = F.tid & 255, tp = (tl & 31) * 2, d8 = (tl >> 5) * 8;
;             const bf16* src = (half ? KBg : KFg) + (size_t)(rc * 64 + tp) * 512 + 64 * h + d8;
;             const v4u w0 = *(const v4u*)src, w1 = *(const v4u*)(src + 512);
;             LAS unsigned* dst = (LAS unsigned*)((half ? KH1 : KH0) + d8 * PITCH + tp);
;             dst[0 * (PITCH / 2)] = (w0.x & 0xffffu) | (w1.x << 16); dst[1 * (PITCH / 2)] = (w0.x >> 16) | (w1.x & 0xffff0000u);
;             dst[2 * (PITCH / 2)] = (w0.y & 0xffffu) | (w1.y << 16); dst[3 * (PITCH / 2)] = (w0.y >> 16) | (w1.y & 0xffff0000u);
;             dst[4 * (PITCH / 2)] = (w0.z & 0xffffu) | (w1.z << 16); dst[5 * (PITCH / 2)] = (w0.z >> 16) | (w1.z & 0xffff0000u);
;             dst[6 * (PITCH / 2)] = (w0.w & 0xffffu) | (w1.w << 16); dst[7 * (PITCH / 2)] = (w0.w >> 16) | (w1.w & 0xffff0000u); }
.LBB0_688:
	v_mov_b32_e32 v42, v247
	s_mov_b64 s[0:1], s[82:83]
	s_load_dwordx2 s[4:5], s[0:1], 0xb0
	v_and_b32_e32 v44, 63, v42
	v_readlane_b32 s8, v254, 28
	v_readlane_b32 s9, v254, 29
	v_lshrrev_b32_e32 v45, 5, v44
	v_readfirstlane_b32 s6, v42
	s_andn2_b64 vcc, exec, s[8:9]
	v_and_b32_e32 v116, 31, v42
	v_lshlrev_b32_e32 v43, 4, v45
	s_cbranch_vccnz .LBB0_697
	s_waitcnt lgkmcnt(0)
	s_add_u32 s8, s4, 0x39c80000
	s_addc_u32 s9, s5, 0
	s_ashr_i32 s20, s6, 8
	s_ashr_i32 s6, s6, 6
	s_and_b32 s12, s6, 3
	v_lshl_or_b32 v2, s12, 5, v116
	v_mul_u32_u24_e32 v2, 0x90, v2
	s_cmp_lt_u32 s6, 4
	v_add3_u32 v46, 0, v2, v43
	v_lshlrev_b32_e32 v2, 1, v42
	s_cselect_b64 s[6:7], -1, 0
	v_and_b32_e32 v48, 62, v2
	v_ashrrev_i32_e32 v2, 2, v42
	s_and_b64 s[10:11], s[6:7], exec
	v_readlane_b32 s13, v255, 4
	v_readlane_b32 s15, v255, 5
	v_and_b32_e32 v36, -8, v2
	s_movk_i32 s3, 0x90
	s_cselect_b32 s10, s13, s15
	v_mul_u32_u24_e32 v4, 0x90, v116
	v_mul_lo_u32 v2, v36, s3
	v_lshlrev_b32_e32 v6, 1, v48
	v_add3_u32 v47, s10, v4, v43
	v_add3_u32 v49, 0, v2, v6
	v_lshrrev_b32_e32 v2, 2, v42
	s_movk_i32 s10, 0x100
	v_and_b32_e32 v4, 56, v2
	v_cmp_gt_u32_e32 vcc, s10, v42
	v_mov_b32_e32 v2, 0x36980000
	v_mov_b32_e32 v7, 0x34780000
	v_cndmask_b32_e32 v2, v2, v7, vcc
	s_lshl_b32 s11, s12, 11
	v_lshlrev_b32_e32 v5, 8, v45
	v_lshl_add_u64 v[38:39], s[4:5], 0, v[2:3]
	v_mov_b32_e32 v2, s15
	v_mov_b32_e32 v7, s13
	v_or3_b32 v5, s11, v5, v116
	v_cndmask_b32_e32 v2, v2, v7, vcc
	v_mul_u32_u24_e32 v7, 0x90, v4
	v_add3_u32 v50, v2, v7, v6
	v_lshlrev_b32_e32 v2, 1, v5
	v_lshl_add_u64 v[6:7], s[4:5], 0, v[2:3]
	s_mov_b64 s[10:11], 0x39d90000
	v_ashrrev_i32_e32 v37, 31, v36
	v_lshl_add_u64 v[40:41], v[6:7], 0, s[10:11]
	v_lshlrev_b32_e32 v2, 1, v4
	v_lshlrev_b32_e32 v51, 2, v116
	s_mov_b32 s21, s2
	s_mov_b32 s32, s21
	s_and_b32 s99, s32, 7
	s_ashr_i32 s32, s32, 3
	v_lshl_or_b32 v76, s32, 6, v48
	v_mov_b64_e32 v[78:79], s[4:5]
	s_movk_i32 s32, 0x3200
	v_ashrrev_i32_e32 v77, 31, v76
	v_mad_i64_i32 v[78:79], vcc, v76, s32, v[78:79]
	s_lshl_b32 s32, s99, 8
	s_nop 0
	v_add_co_u32_e32 v78, vcc, s32, v78
	s_lshl_b32 s32, s99, 7
	s_nop 1
	v_addc_co_u32_e32 v79, vcc, 0, v79, vcc
	v_lshl_add_u64 v[80:81], v[36:37], 1, v[78:79]
	v_lshlrev_b64 v[76:77], 10, v[76:77]
	v_lshl_add_u64 v[76:77], v[38:39], 0, v[76:77]
	v_add_co_u32_e32 v76, vcc, s32, v76
	s_mov_b32 s32, 0x26202000
	s_nop 1
	v_addc_co_u32_e32 v77, vcc, 0, v77, vcc
	v_lshl_add_u64 v[76:77], v[76:77], 0, v[2:3]
	v_add_co_u32_e32 v78, vcc, s32, v80
	s_mov_b32 s32, 0x26205000
	s_nop 1
	v_addc_co_u32_e32 v79, vcc, 0, v81, vcc
	global_load_dwordx4 v[60:63], v[78:79], off
	global_load_dwordx4 v[64:67], v[76:77], off
	v_add_co_u32_e32 v80, vcc, s32, v80
	s_nop 1
	v_addc_co_u32_e32 v81, vcc, 0, v81, vcc
	global_load_dwordx4 v[68:71], v[80:81], off offset:512
	global_load_dwordx4 v[72:75], v[76:77], off offset:1024
	s_waitcnt vmcnt(0)
	s_branch .LBB0_691

; #define LAS __attribute__((address_space(3)))
; __device__ __forceinline__ void ph_g1(Frame& F) {
;     ...
;     for (int u = blockIdx.x; u < NRC * 8; u += F.G) {
;         const int rc = u >> 3, h = u & 7;
;         __syncthreads();
;         stage_vt(F, P, rc, h, VT);
;         {
;             const int half = F.tid >> 8, tl = F.tid & 255, tp = (tl & 31) * 2, d8 = (tl >> 5) * 8;
;             const bf16* src = (half ? KBg : KFg) + (size_t)(rc * 64 + tp) * 512 + 64 * h + d8;
;             const v4u w0 = *(const v4u*)src, w1 = *(const v4u*)(src + 512);
;             LAS unsigned* dst = (LAS unsigned*)((half ? KH1 : KH0) + d8 * PITCH + tp);
;             dst[0 * (PITCH / 2)] = (w0.x & 0xffffu) | (w1.x << 16); dst[1 * (PITCH / 2)] = (w0.x >> 16) | (w1.x & 0xffff0000u);
;             dst[2 * (PITCH / 2)] = (w0.y & 0xffffu) | (w1.y << 16); dst[3 * (PITCH / 2)] = (w0.y >> 16) | (w1.y & 0xffff0000u);
;             dst[4 * (PITCH / 2)] = (w0.z & 0xffffu) | (w1.z << 16); dst[5 * (PITCH / 2)] = (w0.z >> 16) | (w1.z & 0xffff0000u);
;             dst[6 * (PITCH / 2)] = (w0.w & 0xffffu) | (w1.w << 16); dst[7 * (PITCH / 2)] = (w0.w >> 16) | (w1.w & 0xffff0000u); }
;         __syncthreads();
;         const LAS bf16* KH = dir ? KH1 : KH0;
;         f32x16 acc0 = {}, acc1 = {};
; #pragma unroll
;         for (int ks = 0; ks < 4; ++ks) { const bf16x8 a = GLA_FRAG(VT, 32 * db + r32, 16 * ks + 8 * hi);
;             acc0 = __builtin_amdgcn_mfma_f32_32x32x16_bf16(a, GLA_FRAG(KH, r32, 16 * ks + 8 * hi), acc0, 0, 0, 0);
;             acc1 = __builtin_amdgcn_mfma_f32_32x32x16_bf16(a, GLA_FRAG(KH, 32 + r32, 16 * ks + 8 * hi), acc1, 0, 0, 0); }
.LBB0_691:
	s_ashr_i32 s10, s21, 3
	s_and_b32 s22, s21, 7
	s_waitcnt vmcnt(32)
	s_barrier
	v_mov_b32_e32 v4, v60
	v_mov_b32_e32 v5, v61
	v_mov_b32_e32 v6, v62
	v_mov_b32_e32 v7, v63
	v_mov_b32_e32 v8, v64
	v_mov_b32_e32 v9, v65
	v_mov_b32_e32 v10, v66
	v_mov_b32_e32 v11, v67
	v_mov_b32_e32 v12, v68
	v_mov_b32_e32 v13, v69
	v_mov_b32_e32 v14, v70
	v_mov_b32_e32 v15, v71
	v_mov_b32_e32 v16, v72
	v_mov_b32_e32 v17, v73
	v_mov_b32_e32 v18, v74
	v_mov_b32_e32 v19, v75
	s_ashr_i32 s11, s10, 31
	s_lshl_b64 s[18:19], s[10:11], 11
	s_add_u32 s18, s8, s18
	s_addc_u32 s19, s9, s19
	s_lshl_b32 s30, s22, 8
	s_add_u32 s18, s18, s30
	s_addc_u32 s19, s19, 0
	global_load_dword v84, v51, s[18:19]
	global_load_dword v86, v51, s[18:19] offset:128
	v_readlane_b32 s99, v253, 4
	s_nop 3
	s_add_i32 s32, s21, s99
	s_and_b32 s99, s32, 7
	s_ashr_i32 s32, s32, 3
	v_lshl_or_b32 v76, s32, 6, v48
	v_mov_b64_e32 v[78:79], s[4:5]
	s_movk_i32 s32, 0x3200
	v_ashrrev_i32_e32 v77, 31, v76
	v_mad_i64_i32 v[78:79], vcc, v76, s32, v[78:79]
	s_lshl_b32 s32, s99, 8
	s_nop 0
	v_add_co_u32_e32 v78, vcc, s32, v78
	s_lshl_b32 s32, s99, 7
	s_nop 1
	v_addc_co_u32_e32 v79, vcc, 0, v79, vcc
	v_lshl_add_u64 v[80:81], v[36:37], 1, v[78:79]
	v_lshlrev_b64 v[76:77], 10, v[76:77]
	v_lshl_add_u64 v[76:77], v[38:39], 0, v[76:77]
	v_add_co_u32_e32 v76, vcc, s32, v76
	s_mov_b32 s32, 0x26202000
	s_nop 1
	v_addc_co_u32_e32 v77, vcc, 0, v77, vcc
	v_lshl_add_u64 v[76:77], v[76:77], 0, v[2:3]
	v_add_co_u32_e32 v78, vcc, s32, v80
	s_mov_b32 s32, 0x26205000
	s_nop 1
	v_addc_co_u32_e32 v79, vcc, 0, v81, vcc
	global_load_dwordx4 v[60:63], v[78:79], off
	global_load_dwordx4 v[64:67], v[76:77], off
	v_add_co_u32_e32 v80, vcc, s32, v80
	s_nop 1
	v_addc_co_u32_e32 v81, vcc, 0, v81, vcc
	global_load_dwordx4 v[68:71], v[80:81], off offset:512
	global_load_dwordx4 v[72:75], v[76:77], off offset:1024
	s_mov_b32 s3, 0xffff0000
	s_cmpk_lt_i32 s10, 0x100
	s_cselect_b64 s[12:13], -1, 0
	s_cmpk_gt_i32 s10, 0xff
	s_mov_b64 s[18:19], -1
	v_and_b32_e32 v20, 0xffff, v4
	v_lshrrev_b32_e32 v4, 16, v4
	v_and_b32_e32 v21, 0xffff, v5
	v_lshrrev_b32_e32 v5, 16, v5
	v_and_b32_e32 v22, 0xffff, v6
	v_lshrrev_b32_e32 v6, 16, v6
	v_and_b32_e32 v23, 0xffff, v7
	v_lshrrev_b32_e32 v7, 16, v7
	v_and_b32_e32 v24, 0xffff, v8
	v_lshrrev_b32_e32 v8, 16, v8
	v_and_b32_e32 v25, 0xffff, v9
	v_lshrrev_b32_e32 v9, 16, v9
	v_and_b32_e32 v26, 0xffff, v10
	v_lshrrev_b32_e32 v10, 16, v10
	v_and_b32_e32 v27, 0xffff, v11
	v_lshrrev_b32_e32 v11, 16, v11
	v_lshl_or_b32 v20, v12, 16, v20
	v_and_or_b32 v4, v12, s3, v4
	v_and_or_b32 v5, v13, s3, v5
	v_and_or_b32 v6, v14, s3, v6
	v_and_or_b32 v7, v15, s3, v7
	v_lshl_or_b32 v12, v13, 16, v21
	v_lshl_or_b32 v13, v14, 16, v22
	v_lshl_or_b32 v14, v15, 16, v23
	v_lshl_or_b32 v15, v16, 16, v24
	v_and_or_b32 v8, v16, s3, v8
	v_lshl_or_b32 v16, v17, 16, v25
	v_and_or_b32 v9, v17, s3, v9
	v_lshl_or_b32 v17, v18, 16, v26
	v_and_or_b32 v10, v18, s3, v10
	v_lshl_or_b32 v18, v19, 16, v27
	v_and_or_b32 v11, v19, s3, v11
	ds_write2_b32 v49, v20, v4 offset1:36
	ds_write2_b32 v49, v12, v5 offset0:72 offset1:108
	ds_write2_b32 v49, v13, v6 offset0:144 offset1:180
	ds_write2_b32 v49, v14, v7 offset0:216 offset1:252
	ds_write2_b32 v50, v15, v8 offset1:36
	ds_write2_b32 v50, v16, v9 offset0:72 offset1:108
	ds_write2_b32 v50, v17, v10 offset0:144 offset1:180
	ds_write2_b32 v50, v18, v11 offset0:216 offset1:252
	s_waitcnt lgkmcnt(0)
	s_barrier
	ds_read_b128 v[20:23], v46
	ds_read_b128 v[4:7], v47
	s_waitcnt lgkmcnt(0)
	v_mfma_f32_32x32x16_bf16 v[4:19], v[20:23], v[4:7], 0
	ds_read_b128 v[24:27], v47 offset:4608
	ds_read_b128 v[52:55], v46 offset:32
	ds_read_b128 v[56:59], v47 offset:32
	s_waitcnt lgkmcnt(2)
	v_mfma_f32_32x32x16_bf16 v[20:35], v[20:23], v[24:27], 0
	s_waitcnt lgkmcnt(0)
	v_mfma_f32_32x32x16_bf16 v[4:19], v[52:55], v[56:59], v[4:19]
	ds_read_b128 v[56:59], v47 offset:4640
	s_waitcnt lgkmcnt(0)
	v_mfma_f32_32x32x16_bf16 v[20:35], v[52:55], v[56:59], v[20:35]
	ds_read_b128 v[52:55], v46 offset:64
	ds_read_b128 v[56:59], v47 offset:64
	s_waitcnt lgkmcnt(0)
	v_mfma_f32_32x32x16_bf16 v[4:19], v[52:55], v[56:59], v[4:19]
	ds_read_b128 v[56:59], v47 offset:4672
	s_waitcnt lgkmcnt(0)
	v_mfma_f32_32x32x16_bf16 v[20:35], v[52:55], v[56:59], v[20:35]
	ds_read_b128 v[52:55], v46 offset:96
	ds_read_b128 v[56:59], v47 offset:96
	s_waitcnt lgkmcnt(0)
	v_mfma_f32_32x32x16_bf16 v[4:19], v[52:55], v[56:59], v[4:19]
	ds_read_b128 v[56:59], v47 offset:4704
	s_waitcnt lgkmcnt(0)
	v_mfma_f32_32x32x16_bf16 v[20:35], v[52:55], v[56:59], v[20:35]
	s_cbranch_scc1 .LBB0_694
	s_andn2_b64 vcc, exec, s[18:19]
	s_cbranch_vccz .LBB0_695

; __device__ __forceinline__ void ph_g1(Frame& F) {
;     ...
;         const int b = rc_batch(rc), chain = (b * 8 + h) * 2 + dir, slot = rc_slot(rc, dir);
;         if (dir == 0) { const float a0 = AL[(size_t)rc * 512 + 64 * h + r32], a1 = AL[(size_t)rc * 512 + 64 * h + 32 + r32];
; #pragma unroll
;             for (int r = 0; r < 16; ++r) { acc0[r] *= a0; acc1[r] *= a1; } }
.LBB0_696:
	s_waitcnt vmcnt(5)
	v_pk_mul_f32 v[18:19], v[18:19], v[84:85] op_sel_hi:[1,0]
	v_pk_mul_f32 v[16:17], v[16:17], v[84:85] op_sel_hi:[1,0]
	v_pk_mul_f32 v[14:15], v[14:15], v[84:85] op_sel_hi:[1,0]
	v_pk_mul_f32 v[12:13], v[12:13], v[84:85] op_sel_hi:[1,0]
	v_pk_mul_f32 v[10:11], v[10:11], v[84:85] op_sel_hi:[1,0]
	v_pk_mul_f32 v[8:9], v[8:9], v[84:85] op_sel_hi:[1,0]
	v_pk_mul_f32 v[6:7], v[6:7], v[84:85] op_sel_hi:[1,0]
	v_pk_mul_f32 v[4:5], v[4:5], v[84:85] op_sel_hi:[1,0]
	s_waitcnt vmcnt(4)
	v_pk_mul_f32 v[34:35], v[34:35], v[86:87] op_sel_hi:[1,0]
	v_pk_mul_f32 v[32:33], v[32:33], v[86:87] op_sel_hi:[1,0]
	v_pk_mul_f32 v[30:31], v[30:31], v[86:87] op_sel_hi:[1,0]
	v_pk_mul_f32 v[28:29], v[28:29], v[86:87] op_sel_hi:[1,0]
	v_pk_mul_f32 v[26:27], v[26:27], v[86:87] op_sel_hi:[1,0]
	v_pk_mul_f32 v[24:25], v[24:25], v[86:87] op_sel_hi:[1,0]
	v_pk_mul_f32 v[22:23], v[22:23], v[86:87] op_sel_hi:[1,0]
	v_pk_mul_f32 v[20:21], v[20:21], v[86:87] op_sel_hi:[1,0]
	s_branch .LBB0_690
